# v041 + V-sweep epilogue rows and gate vector prefetched at the top of each quarter sweep
# baseline (speedup 1.0000x reference)
.LBB0_109:
	s_lshl_b32 s98, s10, 9
	s_mov_b32 s99, 0
	v_lshlrev_b32_e32 v199, 4, v176
	v_ashrrev_i32_e32 v200, 2, v176
	v_and_b32_e32 v199, 0xf0, v199
	v_and_b32_e32 v200, -8, v200
	v_add_u32_e32 v199, v199, v200
	v_lshrrev_b32_e32 v200, 2, v176
	v_and_or_b32 v200, v200, 4, v199
	v_ashrrev_i32_e32 v201, 31, v200
	v_lshl_add_u64 v[202:203], v[200:201], 1, s[22:23]
	v_lshl_add_u64 v[202:203], v[202:203], 0, s[98:99]
	v_lshl_add_u64 v[204:205], v[202:203], 0, s[38:39]
	global_load_dwordx2 v[228:229], v[204:205], off
	v_lshl_add_u64 v[204:205], v[202:203], 0, s[42:43]
	global_load_dwordx2 v[230:231], v[204:205], off
	v_lshl_add_u64 v[204:205], v[202:203], 0, s[46:47]
	global_load_dwordx2 v[232:233], v[204:205], off
	v_lshl_add_u64 v[204:205], v[202:203], 0, s[50:51]
	global_load_dwordx2 v[234:235], v[204:205], off
	v_lshl_add_u64 v[204:205], v[202:203], 0, s[54:55]
	global_load_dwordx2 v[236:237], v[204:205], off
	v_lshl_add_u64 v[204:205], v[202:203], 0, s[58:59]
	global_load_dwordx2 v[238:239], v[204:205], off
	v_lshl_add_u64 v[204:205], v[202:203], 0, s[64:65]
	global_load_dwordx2 v[240:241], v[204:205], off
	v_lshl_add_u64 v[204:205], v[202:203], 0, s[68:69]
	global_load_dwordx2 v[242:243], v[204:205], off
	s_lshl_b32 s98, s10, 10
	v_lshl_add_u64 v[204:205], v[200:201], 2, s[0:1]
	v_lshl_add_u64 v[204:205], v[204:205], 0, s[98:99]
	global_load_dwordx4 v[244:247], v[204:205], off
	s_xor_b32 s12, s10, s96
	s_and_b32 s12, s12, 1
	s_lshl_b32 s60, s10, 8
	s_cmp_eq_u32 s12, 0
	s_cselect_b64 s[12:13], -1, 0
	s_and_b64 s[14:15], s[12:13], exec
	s_cselect_b32 s14, 0x1f0, 0
	v_add_u32_e32 v1, s14, v183
	ds_read2st64_b32 v[160:161], v1 offset0:2 offset1:8
	ds_read2st64_b32 v[152:153], v1 offset0:14 offset1:20
	ds_read2st64_b32 v[150:151], v1 offset0:26 offset1:32
	ds_read2st64_b32 v[148:149], v1 offset0:38 offset1:44
	s_cselect_b32 s14, 0x1e0, 16
	v_add_u32_e32 v1, s14, v183
	ds_read2st64_b32 v[146:147], v1 offset0:2 offset1:8
	ds_read2st64_b32 v[144:145], v1 offset0:14 offset1:20
	ds_read2st64_b32 v[142:143], v1 offset0:26 offset1:32
	ds_read2st64_b32 v[138:139], v1 offset0:38 offset1:44
	s_waitcnt lgkmcnt(7)
	v_lshlrev_b32_e32 v1, 10, v160
	v_and_b32_e32 v154, 0x3fffc00, v1
	v_lshlrev_b32_e32 v1, 10, v161
	v_lshl_add_u64 v[2:3], v[134:135], 0, v[154:155]
	v_and_b32_e32 v154, 0x3fffc00, v1
	s_waitcnt lgkmcnt(6)
	v_lshlrev_b32_e32 v1, 10, v152
	v_lshl_add_u64 v[2:3], v[2:3], 0, s[60:61]
	v_lshl_add_u64 v[4:5], v[134:135], 0, v[154:155]
	v_and_b32_e32 v154, 0x3fffc00, v1
	v_lshlrev_b32_e32 v1, 10, v153
	v_lshl_add_u64 v[4:5], v[4:5], 0, s[60:61]
	global_load_dwordx4 v[42:45], v[2:3], off
	global_load_dwordx4 v[46:49], v[4:5], off
	v_lshl_add_u64 v[2:3], v[134:135], 0, v[154:155]
	v_and_b32_e32 v154, 0x3fffc00, v1
	s_waitcnt lgkmcnt(5)
	v_lshlrev_b32_e32 v1, 10, v150
	v_lshl_add_u64 v[2:3], v[2:3], 0, s[60:61]
	v_lshl_add_u64 v[4:5], v[134:135], 0, v[154:155]
	v_and_b32_e32 v154, 0x3fffc00, v1
	v_lshlrev_b32_e32 v1, 10, v151
	v_lshl_add_u64 v[4:5], v[4:5], 0, s[60:61]
	global_load_dwordx4 v[50:53], v[2:3], off
	global_load_dwordx4 v[54:57], v[4:5], off
	v_lshl_add_u64 v[2:3], v[134:135], 0, v[154:155]
	v_and_b32_e32 v154, 0x3fffc00, v1
	s_waitcnt lgkmcnt(4)
	v_lshlrev_b32_e32 v1, 10, v148
	v_lshl_add_u64 v[2:3], v[2:3], 0, s[60:61]
	v_lshl_add_u64 v[4:5], v[134:135], 0, v[154:155]
	v_and_b32_e32 v154, 0x3fffc00, v1
	v_lshlrev_b32_e32 v1, 10, v149
	v_lshl_add_u64 v[4:5], v[4:5], 0, s[60:61]
	global_load_dwordx4 v[58:61], v[2:3], off
	global_load_dwordx4 v[62:65], v[4:5], off
	v_lshl_add_u64 v[2:3], v[134:135], 0, v[154:155]
	v_and_b32_e32 v154, 0x3fffc00, v1
	s_waitcnt lgkmcnt(3)
	v_lshlrev_b32_e32 v1, 10, v146
	v_lshl_add_u64 v[2:3], v[2:3], 0, s[60:61]
	v_lshl_add_u64 v[4:5], v[134:135], 0, v[154:155]
	v_and_b32_e32 v154, 0x3fffc00, v1
	v_lshlrev_b32_e32 v1, 10, v147
	v_lshl_add_u64 v[4:5], v[4:5], 0, s[60:61]
	global_load_dwordx4 v[66:69], v[2:3], off
	global_load_dwordx4 v[70:73], v[4:5], off
	v_lshl_add_u64 v[2:3], v[134:135], 0, v[154:155]
	v_and_b32_e32 v154, 0x3fffc00, v1
	s_waitcnt lgkmcnt(2)
	v_lshlrev_b32_e32 v1, 10, v144
	v_lshl_add_u64 v[2:3], v[2:3], 0, s[60:61]
	v_lshl_add_u64 v[4:5], v[134:135], 0, v[154:155]
	v_and_b32_e32 v154, 0x3fffc00, v1
	v_lshlrev_b32_e32 v1, 10, v145
	v_lshl_add_u64 v[4:5], v[4:5], 0, s[60:61]
	global_load_dwordx4 v[74:77], v[2:3], off
	global_load_dwordx4 v[78:81], v[4:5], off
	v_lshl_add_u64 v[2:3], v[134:135], 0, v[154:155]
	v_and_b32_e32 v154, 0x3fffc00, v1
	s_waitcnt lgkmcnt(1)
	v_lshlrev_b32_e32 v1, 10, v142
	v_lshl_add_u64 v[2:3], v[2:3], 0, s[60:61]
	v_lshl_add_u64 v[4:5], v[134:135], 0, v[154:155]
	v_and_b32_e32 v154, 0x3fffc00, v1
	v_lshlrev_b32_e32 v1, 10, v143
	v_lshl_add_u64 v[4:5], v[4:5], 0, s[60:61]
	global_load_dwordx4 v[90:93], v[2:3], off
	global_load_dwordx4 v[94:97], v[4:5], off
	v_lshl_add_u64 v[2:3], v[134:135], 0, v[154:155]
	v_and_b32_e32 v154, 0x3fffc00, v1
	s_waitcnt lgkmcnt(0)
	v_lshlrev_b32_e32 v1, 10, v138
	v_lshl_add_u64 v[2:3], v[2:3], 0, s[60:61]
	v_lshl_add_u64 v[4:5], v[134:135], 0, v[154:155]
	v_and_b32_e32 v154, 0x3fffc00, v1
	v_lshlrev_b32_e32 v1, 10, v139
	v_lshl_add_u64 v[4:5], v[4:5], 0, s[60:61]
	global_load_dwordx4 v[98:101], v[2:3], off
	global_load_dwordx4 v[102:105], v[4:5], off
	v_lshl_add_u64 v[2:3], v[134:135], 0, v[154:155]
	v_and_b32_e32 v154, 0x3fffc00, v1
	v_lshl_add_u64 v[2:3], v[2:3], 0, s[60:61]
	v_lshl_add_u64 v[4:5], v[134:135], 0, v[154:155]
	v_lshl_add_u64 v[4:5], v[4:5], 0, s[60:61]
	global_load_dwordx4 v[106:109], v[2:3], off
	global_load_dwordx4 v[110:113], v[4:5], off
	s_cselect_b32 s14, 0x1d0, 32
	v_add_u32_e32 v1, s14, v183
	s_cselect_b32 s14, 0x1c0, 48
	ds_read2st64_b32 v[136:137], v1 offset0:2 offset1:8
	ds_read2st64_b32 v[162:163], v1 offset0:14 offset1:20
	ds_read2st64_b32 v[164:165], v1 offset0:26 offset1:32
	ds_read2st64_b32 v[166:167], v1 offset0:38 offset1:44
	v_add_u32_e32 v1, s14, v183
	ds_read2st64_b32 v[168:169], v1 offset0:2 offset1:8
	ds_read2st64_b32 v[170:171], v1 offset0:14 offset1:20
	ds_read2st64_b32 v[172:173], v1 offset0:26 offset1:32
	ds_read2st64_b32 v[174:175], v1 offset0:38 offset1:44
	v_mov_b32_e32 v122, 0
	v_lshl_add_u64 v[140:141], v[134:135], 0, s[60:61]
	s_mov_b32 s14, -2
	v_mov_b32_e32 v123, v122
	v_mov_b32_e32 v124, v122
	v_mov_b32_e32 v125, v122
	v_mov_b32_e32 v126, v122
	v_mov_b32_e32 v127, v122
	v_mov_b32_e32 v128, v122
	v_mov_b32_e32 v129, v122
	v_mov_b32_e32 v114, v122
	v_mov_b32_e32 v115, v122
	v_mov_b32_e32 v116, v122
	v_mov_b32_e32 v117, v122
	v_mov_b32_e32 v118, v122
	v_mov_b32_e32 v119, v122
	v_mov_b32_e32 v120, v122
	v_mov_b32_e32 v121, v122
	v_mov_b32_e32 v82, v122
	v_mov_b32_e32 v83, v122
	v_mov_b32_e32 v84, v122
	v_mov_b32_e32 v85, v122
	v_mov_b32_e32 v86, v122
	v_mov_b32_e32 v87, v122
	v_mov_b32_e32 v88, v122
	v_mov_b32_e32 v89, v122
	v_mov_b32_e32 v34, v122
	v_mov_b32_e32 v35, v122
	v_mov_b32_e32 v36, v122
	v_mov_b32_e32 v37, v122
	v_mov_b32_e32 v38, v122
	v_mov_b32_e32 v39, v122
	v_mov_b32_e32 v40, v122
	v_mov_b32_e32 v41, v122
	s_waitcnt vmcnt(26)
	v_mov_b32_e32 v26, v122
	v_mov_b32_e32 v27, v122
	v_mov_b32_e32 v28, v122
	v_mov_b32_e32 v29, v122
	v_mov_b32_e32 v30, v122
	v_mov_b32_e32 v31, v122
	v_mov_b32_e32 v32, v122
	v_mov_b32_e32 v33, v122
	v_mov_b32_e32 v18, v122
	v_mov_b32_e32 v19, v122
	v_mov_b32_e32 v20, v122
	v_mov_b32_e32 v21, v122
	v_mov_b32_e32 v22, v122
	v_mov_b32_e32 v23, v122
	v_mov_b32_e32 v24, v122
	v_mov_b32_e32 v25, v122
	s_waitcnt vmcnt(25)
	v_mov_b32_e32 v10, v122
	v_mov_b32_e32 v11, v122
	v_mov_b32_e32 v12, v122
	v_mov_b32_e32 v13, v122
	v_mov_b32_e32 v14, v122
	v_mov_b32_e32 v15, v122
	v_mov_b32_e32 v16, v122
	v_mov_b32_e32 v17, v122
	v_mov_b32_e32 v2, v122
	v_mov_b32_e32 v3, v122
	v_mov_b32_e32 v4, v122
	v_mov_b32_e32 v5, v122
	v_mov_b32_e32 v6, v122
	v_mov_b32_e32 v7, v122
	v_mov_b32_e32 v8, v122
	v_mov_b32_e32 v9, v122
.LBB0_110:
	v_bfe_u32 v154, v160, v182, 8
	s_waitcnt lgkmcnt(7)
	v_mov_b32_e32 v196, v137
	v_mov_b32_e32 v198, v136
	v_lshlrev_b64 v[136:137], v132, v[154:155]
	s_barrier
	s_add_i32 s14, s14, 2
	s_waitcnt vmcnt(11)
	v_mfma_f32_16x16x32_fp8_fp8 v[122:125], v[136:137], v[42:43], v[122:125]
	v_lshlrev_b32_e32 v42, 10, v198
	v_and_b32_e32 v154, 0x3fffc00, v42
	v_lshl_add_u64 v[42:43], v[140:141], 0, v[154:155]
	v_mfma_f32_16x16x32_fp8_fp8 v[126:129], v[136:137], v[44:45], v[126:129]
	global_load_dwordx4 v[42:45], v[42:43], off
	s_min_u32 s15, s14, 27
	s_add_i32 s18, s15, 4
	s_sub_i32 s15, 27, s15
	s_and_b64 s[16:17], s[12:13], exec
	s_cselect_b32 s15, s15, s18
	s_waitcnt lgkmcnt(4)
	v_mov_b32_e32 v184, v167
	v_lshl_add_u32 v167, s15, 4, v183
	ds_read_b32 v136, v167 offset:512
	s_waitcnt lgkmcnt(1)
	v_mov_b32_e32 v1, v175
	v_mov_b32_e32 v185, v174
	v_mov_b32_e32 v186, v166
	v_mov_b32_e32 v187, v173
	v_mov_b32_e32 v188, v165
	v_mov_b32_e32 v189, v172
	v_mov_b32_e32 v190, v164
	v_mov_b32_e32 v191, v171
	v_mov_b32_e32 v192, v163
	v_mov_b32_e32 v193, v170
	v_mov_b32_e32 v194, v162
	v_mov_b32_e32 v195, v169
	v_mov_b32_e32 v197, v168
	v_bfe_u32 v154, v161, v182, 8
	v_lshlrev_b64 v[160:161], v132, v[154:155]
	ds_read_b32 v137, v167 offset:2048
	s_waitcnt vmcnt(11)
	v_mfma_f32_16x16x32_fp8_fp8 v[114:117], v[160:161], v[46:47], v[114:117]
	v_lshlrev_b32_e32 v46, 10, v196
	v_and_b32_e32 v154, 0x3fffc00, v46
	v_lshl_add_u64 v[46:47], v[140:141], 0, v[154:155]
	v_mfma_f32_16x16x32_fp8_fp8 v[118:121], v[160:161], v[48:49], v[118:121]
	global_load_dwordx4 v[46:49], v[46:47], off
	v_bfe_u32 v154, v152, v182, 8
	v_lshlrev_b64 v[160:161], v132, v[154:155]
	ds_read_b32 v162, v167 offset:3584
	s_waitcnt vmcnt(11)
	v_mfma_f32_16x16x32_fp8_fp8 v[82:85], v[160:161], v[50:51], v[82:85]
	v_lshlrev_b32_e32 v50, 10, v194
	v_and_b32_e32 v154, 0x3fffc00, v50
	v_lshl_add_u64 v[50:51], v[140:141], 0, v[154:155]
	v_mfma_f32_16x16x32_fp8_fp8 v[86:89], v[160:161], v[52:53], v[86:89]
	global_load_dwordx4 v[50:53], v[50:51], off
	v_bfe_u32 v154, v153, v182, 8
	v_lshlrev_b64 v[152:153], v132, v[154:155]
	ds_read_b32 v163, v167 offset:5120
	s_waitcnt vmcnt(11)
	v_mfma_f32_16x16x32_fp8_fp8 v[34:37], v[152:153], v[54:55], v[34:37]
	v_lshlrev_b32_e32 v54, 10, v192
	v_and_b32_e32 v154, 0x3fffc00, v54
	v_lshl_add_u64 v[54:55], v[140:141], 0, v[154:155]
	v_mfma_f32_16x16x32_fp8_fp8 v[38:41], v[152:153], v[56:57], v[38:41]
	global_load_dwordx4 v[54:57], v[54:55], off
	v_bfe_u32 v154, v150, v182, 8
	v_lshlrev_b64 v[152:153], v132, v[154:155]
	ds_read_b32 v164, v167 offset:6656
	s_waitcnt vmcnt(11)
	v_mfma_f32_16x16x32_fp8_fp8 v[26:29], v[152:153], v[58:59], v[26:29]
	v_lshlrev_b32_e32 v58, 10, v190
	v_and_b32_e32 v154, 0x3fffc00, v58
	v_lshl_add_u64 v[58:59], v[140:141], 0, v[154:155]
	v_mfma_f32_16x16x32_fp8_fp8 v[30:33], v[152:153], v[60:61], v[30:33]
	global_load_dwordx4 v[58:61], v[58:59], off
	v_bfe_u32 v154, v151, v182, 8
	v_lshlrev_b64 v[150:151], v132, v[154:155]
	ds_read_b32 v165, v167 offset:8192
	s_waitcnt vmcnt(11)
	v_mfma_f32_16x16x32_fp8_fp8 v[18:21], v[150:151], v[62:63], v[18:21]
	v_lshlrev_b32_e32 v62, 10, v188
	v_and_b32_e32 v154, 0x3fffc00, v62
	v_lshl_add_u64 v[62:63], v[140:141], 0, v[154:155]
	v_mfma_f32_16x16x32_fp8_fp8 v[22:25], v[150:151], v[64:65], v[22:25]
	global_load_dwordx4 v[62:65], v[62:63], off
	v_bfe_u32 v154, v148, v182, 8
	v_lshlrev_b64 v[150:151], v132, v[154:155]
	ds_read_b32 v166, v167 offset:9728
	s_waitcnt vmcnt(11)
	v_mfma_f32_16x16x32_fp8_fp8 v[10:13], v[150:151], v[66:67], v[10:13]
	v_lshlrev_b32_e32 v66, 10, v186
	v_and_b32_e32 v154, 0x3fffc00, v66
	v_lshl_add_u64 v[66:67], v[140:141], 0, v[154:155]
	v_mfma_f32_16x16x32_fp8_fp8 v[14:17], v[150:151], v[68:69], v[14:17]
	global_load_dwordx4 v[66:69], v[66:67], off
	v_bfe_u32 v154, v149, v182, 8
	v_lshlrev_b64 v[148:149], v132, v[154:155]
	ds_read_b32 v167, v167 offset:11264
	s_waitcnt vmcnt(11)
	v_mfma_f32_16x16x32_fp8_fp8 v[2:5], v[148:149], v[70:71], v[2:5]
	v_lshlrev_b32_e32 v70, 10, v184
	v_and_b32_e32 v154, 0x3fffc00, v70
	v_lshl_add_u64 v[70:71], v[140:141], 0, v[154:155]
	v_mfma_f32_16x16x32_fp8_fp8 v[6:9], v[148:149], v[72:73], v[6:9]
	global_load_dwordx4 v[70:73], v[70:71], off
	v_bfe_u32 v154, v146, v182, 8
	v_lshlrev_b64 v[148:149], v132, v[154:155]
	s_min_u32 s15, s14, 26
	s_add_i32 s18, s15, 5
	s_sub_i32 s15, 26, s15
	s_and_b64 s[16:17], s[12:13], exec
	s_waitcnt vmcnt(11)
	v_mfma_f32_16x16x32_fp8_fp8 v[122:125], v[148:149], v[74:75], v[122:125]
	v_lshlrev_b32_e32 v74, 10, v197
	v_and_b32_e32 v154, 0x3fffc00, v74
	v_lshl_add_u64 v[74:75], v[140:141], 0, v[154:155]
	v_mfma_f32_16x16x32_fp8_fp8 v[126:129], v[148:149], v[76:77], v[126:129]
	global_load_dwordx4 v[74:77], v[74:75], off
	s_cselect_b32 s15, s15, s18
	v_lshl_add_u32 v148, s15, 4, v183
	ds_read_b32 v168, v148 offset:512
	v_bfe_u32 v154, v147, v182, 8
	v_lshlrev_b64 v[146:147], v132, v[154:155]
	ds_read_b32 v169, v148 offset:2048
	s_waitcnt vmcnt(11)
	v_mfma_f32_16x16x32_fp8_fp8 v[114:117], v[146:147], v[78:79], v[114:117]
	v_lshlrev_b32_e32 v78, 10, v195
	v_and_b32_e32 v154, 0x3fffc00, v78
	v_lshl_add_u64 v[78:79], v[140:141], 0, v[154:155]
	v_mfma_f32_16x16x32_fp8_fp8 v[118:121], v[146:147], v[80:81], v[118:121]
	global_load_dwordx4 v[78:81], v[78:79], off
	v_bfe_u32 v154, v144, v182, 8
	v_lshlrev_b64 v[146:147], v132, v[154:155]
	ds_read_b32 v170, v148 offset:3584
	s_waitcnt vmcnt(11)
	v_mfma_f32_16x16x32_fp8_fp8 v[82:85], v[146:147], v[90:91], v[82:85]
	v_lshlrev_b32_e32 v90, 10, v193
	v_and_b32_e32 v154, 0x3fffc00, v90
	v_lshl_add_u64 v[90:91], v[140:141], 0, v[154:155]
	v_mfma_f32_16x16x32_fp8_fp8 v[86:89], v[146:147], v[92:93], v[86:89]
	global_load_dwordx4 v[90:93], v[90:91], off
	v_bfe_u32 v154, v145, v182, 8
	v_lshlrev_b64 v[144:145], v132, v[154:155]
	ds_read_b32 v171, v148 offset:5120
	s_waitcnt vmcnt(11)
	v_mfma_f32_16x16x32_fp8_fp8 v[34:37], v[144:145], v[94:95], v[34:37]
	v_lshlrev_b32_e32 v94, 10, v191
	v_and_b32_e32 v154, 0x3fffc00, v94
	v_lshl_add_u64 v[94:95], v[140:141], 0, v[154:155]
	v_mfma_f32_16x16x32_fp8_fp8 v[38:41], v[144:145], v[96:97], v[38:41]
	global_load_dwordx4 v[94:97], v[94:95], off
	v_bfe_u32 v154, v142, v182, 8
	v_lshlrev_b64 v[144:145], v132, v[154:155]
	ds_read_b32 v172, v148 offset:6656
	s_waitcnt vmcnt(11)
	v_mfma_f32_16x16x32_fp8_fp8 v[26:29], v[144:145], v[98:99], v[26:29]
	v_lshlrev_b32_e32 v98, 10, v189
	v_and_b32_e32 v154, 0x3fffc00, v98
	v_lshl_add_u64 v[98:99], v[140:141], 0, v[154:155]
	v_mfma_f32_16x16x32_fp8_fp8 v[30:33], v[144:145], v[100:101], v[30:33]
	global_load_dwordx4 v[98:101], v[98:99], off
	v_bfe_u32 v154, v143, v182, 8
	v_lshlrev_b64 v[142:143], v132, v[154:155]
	ds_read_b32 v173, v148 offset:8192
	s_waitcnt vmcnt(11)
	v_mfma_f32_16x16x32_fp8_fp8 v[18:21], v[142:143], v[102:103], v[18:21]
	v_lshlrev_b32_e32 v102, 10, v187
	v_and_b32_e32 v154, 0x3fffc00, v102
	v_lshl_add_u64 v[102:103], v[140:141], 0, v[154:155]
	v_mfma_f32_16x16x32_fp8_fp8 v[22:25], v[142:143], v[104:105], v[22:25]
	global_load_dwordx4 v[102:105], v[102:103], off
	v_bfe_u32 v154, v138, v182, 8
	v_lshlrev_b64 v[142:143], v132, v[154:155]
	ds_read_b32 v174, v148 offset:9728
	s_waitcnt vmcnt(11)
	v_mfma_f32_16x16x32_fp8_fp8 v[10:13], v[142:143], v[106:107], v[10:13]
	v_lshlrev_b32_e32 v106, 10, v185
	v_and_b32_e32 v154, 0x3fffc00, v106
	v_lshl_add_u64 v[106:107], v[140:141], 0, v[154:155]
	v_mfma_f32_16x16x32_fp8_fp8 v[14:17], v[142:143], v[108:109], v[14:17]
	global_load_dwordx4 v[106:109], v[106:107], off
	v_bfe_u32 v154, v139, v182, 8
	v_lshlrev_b64 v[138:139], v132, v[154:155]
	ds_read_b32 v175, v148 offset:11264
	s_waitcnt vmcnt(11)
	v_mfma_f32_16x16x32_fp8_fp8 v[2:5], v[138:139], v[110:111], v[2:5]
	v_lshlrev_b32_e32 v110, 10, v1
	v_and_b32_e32 v154, 0x3fffc00, v110
	v_lshl_add_u64 v[110:111], v[140:141], 0, v[154:155]
	v_mfma_f32_16x16x32_fp8_fp8 v[6:9], v[138:139], v[112:113], v[6:9]
	global_load_dwordx4 v[110:113], v[110:111], off
	s_cmp_gt_u32 s14, 29
	v_mov_b32_e32 v160, v198
	v_mov_b32_e32 v146, v197
	v_mov_b32_e32 v161, v196
	v_mov_b32_e32 v147, v195
	v_mov_b32_e32 v152, v194
	v_mov_b32_e32 v144, v193
	v_mov_b32_e32 v153, v192
	v_mov_b32_e32 v145, v191
	v_mov_b32_e32 v150, v190
	v_mov_b32_e32 v142, v189
	v_mov_b32_e32 v151, v188
	v_mov_b32_e32 v143, v187
	v_mov_b32_e32 v148, v186
	v_mov_b32_e32 v138, v185
	v_mov_b32_e32 v149, v184
	v_mov_b32_e32 v139, v1
	s_cbranch_scc0 .LBB0_110
	v_mov_b32_e32 v1, v176
	s_add_i32 s10, s10, 1
	s_waitcnt vmcnt(15)
	v_lshlrev_b32_e32 v42, 4, v1
	v_ashrrev_i32_e32 v43, 2, v1
	v_and_b32_e32 v42, 0xf0, v42
	v_and_b32_e32 v43, -8, v43
	v_add_u32_e32 v42, v42, v43
	v_lshrrev_b32_e32 v1, 2, v1
	s_waitcnt vmcnt(14)
	v_and_or_b32 v46, v1, 4, v42
	v_ashrrev_i32_e32 v47, 31, v46
	v_lshl_add_u64 v[42:43], v[46:47], 2, s[0:1]
	v_lshl_add_u64 v[42:43], s[60:61], 2, v[42:43]
	v_lshl_add_u64 v[46:47], v[46:47], 1, s[22:23]
	s_lshl_b32 s60, s60, 1
	v_lshl_add_u64 v[46:47], v[46:47], 0, s[60:61]
	s_waitcnt vmcnt(7)
	v_lshl_add_u64 v[74:75], v[46:47], 0, s[38:39]
	s_waitcnt vmcnt(0)
	v_mov_b32_e32 v76, v228
	v_mov_b32_e32 v77, v229
	v_lshl_add_u64 v[70:71], v[46:47], 0, s[42:43]
	v_mov_b32_e32 v42, v244
	v_mov_b32_e32 v43, v245
	v_mov_b32_e32 v44, v246
	v_mov_b32_e32 v45, v247
	v_lshl_add_u64 v[66:67], v[46:47], 0, s[46:47]
	v_mov_b32_e32 v72, v230
	v_mov_b32_e32 v73, v231
	v_mov_b32_e32 v68, v232
	v_mov_b32_e32 v69, v233
	v_lshl_add_u64 v[62:63], v[46:47], 0, s[50:51]
	v_mov_b32_e32 v64, v234
	v_mov_b32_e32 v65, v235
	v_lshl_add_u64 v[58:59], v[46:47], 0, s[54:55]
	v_mov_b32_e32 v60, v236
	v_mov_b32_e32 v61, v237
	v_lshl_add_u64 v[54:55], v[46:47], 0, s[58:59]
	v_mov_b32_e32 v56, v238
	v_mov_b32_e32 v57, v239
	v_lshl_add_u64 v[50:51], v[46:47], 0, s[64:65]
	v_mov_b32_e32 v52, v240
	v_mov_b32_e32 v53, v241
	v_lshl_add_u64 v[46:47], v[46:47], 0, s[68:69]
	v_mov_b32_e32 v48, v242
	v_mov_b32_e32 v49, v243
	v_mov_b32_e32 v1, s93
	s_waitcnt vmcnt(15)
	ds_read_b32 v78, v1 offset:14336
	s_nop 1
	v_permlane32_swap_b32 v122, v126
	s_nop 1
	v_permlane32_swap_b32 v123, v127
	s_nop 1
	v_permlane32_swap_b32 v124, v128
	s_nop 1
	v_permlane32_swap_b32 v125, v129
	s_cmp_eq_u32 s10, 4
	v_pk_add_f32 v[80:81], v[122:123], v[126:127]
	s_waitcnt vmcnt(14)
	v_pk_add_f32 v[90:91], v[124:125], v[128:129]
	s_waitcnt lgkmcnt(0)
	v_pk_mul_f32 v[80:81], v[78:79], v[80:81] op_sel_hi:[0,1]
	v_pk_mul_f32 v[78:79], v[78:79], v[90:91] op_sel_hi:[0,1]
	s_waitcnt vmcnt(8)
	v_lshlrev_b32_e32 v90, 16, v76
	v_and_b32_e32 v91, 0xffff0000, v76
	v_lshlrev_b32_e32 v76, 16, v77
	v_and_b32_e32 v77, 0xffff0000, v77
	s_waitcnt vmcnt(7)
	v_pk_fma_f32 v[76:77], v[44:45], v[78:79], v[76:77]
	v_pk_fma_f32 v[78:79], v[42:43], v[80:81], v[90:91]
	s_nop 0
	v_cvt_pk_bf16_f32 v78, v78, v79
	v_cvt_pk_bf16_f32 v79, v76, v77
	global_store_dwordx2 v[74:75], v[78:79], off
	ds_read_b32 v74, v1 offset:14340
	s_nop 1
	v_permlane32_swap_b32 v114, v118
	s_nop 1
	v_permlane32_swap_b32 v115, v119
	s_nop 1
	v_permlane32_swap_b32 v116, v120
	s_nop 1
	v_permlane32_swap_b32 v117, v121
	s_nop 0
	v_pk_add_f32 v[76:77], v[114:115], v[118:119]
	v_pk_add_f32 v[78:79], v[116:117], v[120:121]
	s_waitcnt lgkmcnt(0)
	v_pk_mul_f32 v[76:77], v[74:75], v[76:77] op_sel_hi:[0,1]
	v_pk_mul_f32 v[74:75], v[74:75], v[78:79] op_sel_hi:[0,1]
	s_waitcnt vmcnt(7)
	v_lshlrev_b32_e32 v78, 16, v72
	v_and_b32_e32 v79, 0xffff0000, v72
	v_lshlrev_b32_e32 v72, 16, v73
	v_and_b32_e32 v73, 0xffff0000, v73
	v_pk_fma_f32 v[72:73], v[44:45], v[74:75], v[72:73]
	v_pk_fma_f32 v[74:75], v[42:43], v[76:77], v[78:79]
	s_nop 0
	v_cvt_pk_bf16_f32 v74, v74, v75
	v_cvt_pk_bf16_f32 v75, v72, v73
	global_store_dwordx2 v[70:71], v[74:75], off
	ds_read_b32 v70, v1 offset:14344
	s_nop 1
	v_permlane32_swap_b32 v82, v86
	s_nop 1
	v_permlane32_swap_b32 v83, v87
	s_nop 1
	v_permlane32_swap_b32 v84, v88
	s_nop 1
	v_permlane32_swap_b32 v85, v89
	s_nop 0
	v_pk_add_f32 v[72:73], v[82:83], v[86:87]
	v_pk_add_f32 v[74:75], v[84:85], v[88:89]
	s_waitcnt lgkmcnt(0)
	v_pk_mul_f32 v[72:73], v[70:71], v[72:73] op_sel_hi:[0,1]
	v_pk_mul_f32 v[70:71], v[70:71], v[74:75] op_sel_hi:[0,1]
	s_waitcnt vmcnt(7)
	v_lshlrev_b32_e32 v74, 16, v68
	v_and_b32_e32 v75, 0xffff0000, v68
	v_lshlrev_b32_e32 v68, 16, v69
	v_and_b32_e32 v69, 0xffff0000, v69
	v_pk_fma_f32 v[68:69], v[44:45], v[70:71], v[68:69]
	v_pk_fma_f32 v[70:71], v[42:43], v[72:73], v[74:75]
	s_nop 0
	v_cvt_pk_bf16_f32 v70, v70, v71
	v_cvt_pk_bf16_f32 v71, v68, v69
	global_store_dwordx2 v[66:67], v[70:71], off
	ds_read_b32 v66, v1 offset:14348
	s_nop 1
	v_permlane32_swap_b32 v34, v38
	s_nop 1
	v_permlane32_swap_b32 v35, v39
	s_nop 1
	v_permlane32_swap_b32 v36, v40
	s_nop 1
	v_permlane32_swap_b32 v37, v41
	s_nop 0
	v_pk_add_f32 v[34:35], v[34:35], v[38:39]
	s_waitcnt vmcnt(7)
	v_lshlrev_b32_e32 v38, 16, v64
	s_waitcnt lgkmcnt(0)
	v_pk_mul_f32 v[34:35], v[66:67], v[34:35] op_sel_hi:[0,1]
	v_and_b32_e32 v39, 0xffff0000, v64
	v_pk_add_f32 v[36:37], v[36:37], v[40:41]
	v_pk_fma_f32 v[34:35], v[42:43], v[34:35], v[38:39]
	v_pk_mul_f32 v[36:37], v[66:67], v[36:37] op_sel_hi:[0,1]
	v_lshlrev_b32_e32 v40, 16, v65
	v_and_b32_e32 v41, 0xffff0000, v65
	v_cvt_pk_bf16_f32 v34, v34, v35
	v_pk_fma_f32 v[36:37], v[44:45], v[36:37], v[40:41]
	s_nop 0
	v_cvt_pk_bf16_f32 v35, v36, v37
	global_store_dwordx2 v[62:63], v[34:35], off
	ds_read_b32 v34, v1 offset:14352
	s_nop 1
	v_permlane32_swap_b32 v26, v30
	s_nop 1
	v_permlane32_swap_b32 v27, v31
	s_nop 1
	v_permlane32_swap_b32 v28, v32
	s_nop 1
	v_permlane32_swap_b32 v29, v33
	s_nop 0
	v_pk_add_f32 v[26:27], v[26:27], v[30:31]
	s_waitcnt vmcnt(7)
	v_lshlrev_b32_e32 v30, 16, v60
	s_waitcnt lgkmcnt(0)
	v_pk_mul_f32 v[26:27], v[34:35], v[26:27] op_sel_hi:[0,1]
	v_and_b32_e32 v31, 0xffff0000, v60
	v_pk_add_f32 v[28:29], v[28:29], v[32:33]
	v_pk_fma_f32 v[26:27], v[42:43], v[26:27], v[30:31]
	v_pk_mul_f32 v[28:29], v[34:35], v[28:29] op_sel_hi:[0,1]
	v_lshlrev_b32_e32 v32, 16, v61
	v_and_b32_e32 v33, 0xffff0000, v61
	v_cvt_pk_bf16_f32 v26, v26, v27
	v_pk_fma_f32 v[28:29], v[44:45], v[28:29], v[32:33]
	s_nop 0
	v_cvt_pk_bf16_f32 v27, v28, v29
	global_store_dwordx2 v[58:59], v[26:27], off
	ds_read_b32 v26, v1 offset:14356
	s_nop 1
	v_permlane32_swap_b32 v18, v22
	s_nop 1
	v_permlane32_swap_b32 v19, v23
	s_nop 1
	v_permlane32_swap_b32 v20, v24
	s_nop 1
	v_permlane32_swap_b32 v21, v25
	s_nop 0
	v_pk_add_f32 v[18:19], v[18:19], v[22:23]
	s_waitcnt vmcnt(7)
	v_lshlrev_b32_e32 v22, 16, v56
	s_waitcnt lgkmcnt(0)
	v_pk_mul_f32 v[18:19], v[26:27], v[18:19] op_sel_hi:[0,1]
	v_and_b32_e32 v23, 0xffff0000, v56
	v_pk_add_f32 v[20:21], v[20:21], v[24:25]
	v_pk_fma_f32 v[18:19], v[42:43], v[18:19], v[22:23]
	v_pk_mul_f32 v[20:21], v[26:27], v[20:21] op_sel_hi:[0,1]
	v_lshlrev_b32_e32 v24, 16, v57
	v_and_b32_e32 v25, 0xffff0000, v57
	v_cvt_pk_bf16_f32 v18, v18, v19
	v_pk_fma_f32 v[20:21], v[44:45], v[20:21], v[24:25]
	s_nop 0
	v_cvt_pk_bf16_f32 v19, v20, v21
	global_store_dwordx2 v[54:55], v[18:19], off
	ds_read_b32 v18, v1 offset:14360
	s_nop 1
	v_permlane32_swap_b32 v10, v14
	s_nop 1
	v_permlane32_swap_b32 v11, v15
	s_nop 1
	v_permlane32_swap_b32 v12, v16
	s_nop 1
	v_permlane32_swap_b32 v13, v17
	s_nop 0
	v_pk_add_f32 v[10:11], v[10:11], v[14:15]
	s_waitcnt vmcnt(7)
	v_lshlrev_b32_e32 v14, 16, v52
	s_waitcnt lgkmcnt(0)
	v_pk_mul_f32 v[10:11], v[18:19], v[10:11] op_sel_hi:[0,1]
	v_and_b32_e32 v15, 0xffff0000, v52
	v_pk_add_f32 v[12:13], v[12:13], v[16:17]
	v_pk_fma_f32 v[10:11], v[42:43], v[10:11], v[14:15]
	v_pk_mul_f32 v[12:13], v[18:19], v[12:13] op_sel_hi:[0,1]
	v_lshlrev_b32_e32 v16, 16, v53
	v_and_b32_e32 v17, 0xffff0000, v53
	v_cvt_pk_bf16_f32 v10, v10, v11
	v_pk_fma_f32 v[12:13], v[44:45], v[12:13], v[16:17]
	s_nop 0
	v_cvt_pk_bf16_f32 v11, v12, v13
	global_store_dwordx2 v[50:51], v[10:11], off
	ds_read_b32 v10, v1 offset:14364
	s_nop 1
	v_permlane32_swap_b32 v2, v6
	s_nop 1
	v_permlane32_swap_b32 v3, v7
	s_nop 1
	v_permlane32_swap_b32 v4, v8
	s_nop 1
	v_permlane32_swap_b32 v5, v9
	s_nop 0
	v_pk_add_f32 v[2:3], v[2:3], v[6:7]
	v_pk_add_f32 v[4:5], v[4:5], v[8:9]
	s_waitcnt lgkmcnt(0)
	v_pk_mul_f32 v[2:3], v[10:11], v[2:3] op_sel_hi:[0,1]
	s_waitcnt vmcnt(7)
	v_lshlrev_b32_e32 v6, 16, v48
	v_and_b32_e32 v7, 0xffff0000, v48
	v_pk_mul_f32 v[4:5], v[10:11], v[4:5] op_sel_hi:[0,1]
	v_lshlrev_b32_e32 v8, 16, v49
	v_and_b32_e32 v9, 0xffff0000, v49
	v_pk_fma_f32 v[2:3], v[42:43], v[2:3], v[6:7]
	v_pk_fma_f32 v[4:5], v[44:45], v[4:5], v[8:9]
	v_cvt_pk_bf16_f32 v2, v2, v3
	s_nop 0
	v_cvt_pk_bf16_f32 v3, v4, v5
	global_store_dwordx2 v[46:47], v[2:3], off
	s_cbranch_scc0 .LBB0_109
	v_mov_b32_e32 v1, v176
	s_add_i32 s0, s11, 3
	s_waitcnt vmcnt(0)
	s_mul_hi_u32 s1, s0, 0x6000
	v_lshlrev_b32_e32 v2, 4, v1
	v_ashrrev_i32_e32 v3, 2, v1
	s_mulk_i32 s0, 0x6000
	v_readlane_b32 s10, v254, 29
	v_and_b32_e32 v2, 0xf0, v2
	v_and_b32_e32 v3, -8, v3
	s_add_u32 s0, s10, s0
	v_readlane_b32 s10, v254, 30
	v_add_u32_e32 v2, v2, v3
	v_lshrrev_b32_e32 v1, 2, v1
	s_addc_u32 s1, s10, s1
	v_readlane_b32 s10, v254, 25
	v_and_or_b32 v34, v1, 4, v2
	v_readlane_b32 s11, v254, 26
	v_ashrrev_i32_e32 v35, 31, v34
	s_mov_b64 s[12:13], -1
	s_and_b64 vcc, exec, s[10:11]
	s_cbranch_vccz .LBB0_114
	v_mov_b32_e32 v1, 0xd0
	v_readlane_b32 s12, v254, 23
	v_add_u32_e32 v1, 0, v1
	v_add_u32_e32 v1, 0x20200, v1
	ds_read_b32 v2, v1
	ds_read_b32 v1, v1 offset:4
	v_readlane_b32 s13, v254, 24
	s_add_u32 s12, s12, 0
	s_waitcnt lgkmcnt(1)
	v_readfirstlane_b32 s10, v2
	s_waitcnt lgkmcnt(0)
	v_readfirstlane_b32 s11, v1
	s_addc_u32 s11, s13, s11
	s_add_u32 s10, s12, s10
	s_addc_u32 s11, s11, 0
	v_lshl_add_u64 v[2:3], v[34:35], 2, s[10:11]
	global_load_dwordx4 v[2:5], v[2:3], off
	s_mov_b64 s[12:13], 0
